# speedup vs baseline: 1.0082x; 1.0082x over previous
; #define ATT_DMA(t, b) do { \
;         _Pragma("unroll") for (int i_ = 0; i_ < 2; ++i_) glds16(Kg + (size_t)(t) * 64 * ZP + offK[i_], lds + (b) * BUF + (i_ * 8 + wid) * 1024); \
;         _Pragma("unroll") for (int i_ = 0; i_ < 2; ++i_) glds16(Vg + (size_t)(t) * 64 + offV[i_], lds + (b) * BUF + KBYTES + (i_ * 8 + wid) * 1024); } while (0)
; __device__ __forceinline__ void attn_phase(LAS unsigned char* lds, const bf16_t* Z, const bf16_t* VT, bf16_t* Y, const float* subln, float lam, float lam_init, float M0, unsigned* ctr, LAS int* s_unit, int wid_s_) {
;     ...
;         const int Tlo = tlo >> 1, Thi = thi >> 1;
;         ATT_DMA(2 * Tlo, 0); ATT_DMA(2 * Tlo + 1, 1);
;         for (int T = Tlo; T <= Thi; ++T) {
;             const int b = (T - Tlo) & 1;
;             asm volatile("s_waitcnt vmcnt(0)" ::: "memory");
;             __syncthreads();
;             if (T + 1 <= Thi) { ATT_DMA(2 * T + 2, 2 * (b ^ 1)); ATT_DMA(2 * T + 3, 2 * (b ^ 1) + 1); }
.LBB0_1299:
	s_waitcnt vmcnt(0)
	s_and_b32 s17, s49, 1
	s_lshl_b32 s16, s17, 16
	s_waitcnt lgkmcnt(0)
	s_barrier
	s_bitcmp1_b32 s37, 12
	s_cbranch_scc1 .LBB0_1303
	s_add_i32 s2, s15, s49
	s_cmp_lt_i32 s2, s48
	s_cbranch_scc0 .LBB0_1303
	s_xor_b32 s2, s16, 0x10000
	s_add_i32 s2, s37, s2
	v_lshl_add_u64 v[64:65], s[28:29], 0, v[182:183]
	v_lshl_add_u64 v[66:67], v[64:65], 0, s[68:69]
	s_mov_b32 m0, s2
	v_lshl_add_u64 v[64:65], v[64:65], 0, s[72:73]
	global_load_lds_dwordx4 v[66:67], off
	v_lshl_add_u64 v[66:67], s[28:29], 0, v[180:181]
	v_lshl_add_u64 v[68:69], v[66:67], 0, s[68:69]
	s_add_i32 m0, s2, 0x2000
	s_nop 0
	global_load_lds_dwordx4 v[68:69], off
	v_lshl_add_u64 v[68:69], s[28:29], 0, v[178:179]
	s_add_i32 m0, s2, 0x4000
	v_lshl_add_u64 v[70:71], v[68:69], 0, s[70:71]
	global_load_lds_dwordx4 v[70:71], off
	v_lshl_add_u64 v[70:71], s[28:29], 0, v[176:177]
	v_lshl_add_u64 v[72:73], v[70:71], 0, s[70:71]
	s_add_i32 m0, s2, 0x6000
	s_nop 0
	global_load_lds_dwordx4 v[72:73], off
	s_add_i32 m0, s2, 0x8000
	s_nop 0
	global_load_lds_dwordx4 v[64:65], off
	v_lshl_add_u64 v[64:65], v[66:67], 0, s[72:73]
	s_add_i32 m0, s2, 0xa000
	s_nop 0
	global_load_lds_dwordx4 v[64:65], off
	s_add_i32 m0, s2, 0xc000
	v_lshl_add_u64 v[64:65], v[68:69], 0, s[76:77]
	global_load_lds_dwordx4 v[64:65], off
	v_lshl_add_u64 v[64:65], v[70:71], 0, s[76:77]
	s_add_i32 m0, s2, 0xe000
	s_nop 0
	global_load_lds_dwordx4 v[64:65], off

; #define ATT_DMA(t, b) do { \
;         _Pragma("unroll") for (int i_ = 0; i_ < 2; ++i_) glds16(Kg + (size_t)(t) * 64 * ZP + offK[i_], lds + (b) * BUF + (i_ * 8 + wid) * 1024); \
;         _Pragma("unroll") for (int i_ = 0; i_ < 2; ++i_) glds16(Vg + (size_t)(t) * 64 + offV[i_], lds + (b) * BUF + KBYTES + (i_ * 8 + wid) * 1024); } while (0)
; __device__ __forceinline__ void attn_phase(LAS unsigned char* lds, const bf16_t* Z, const bf16_t* VT, bf16_t* Y, const float* subln, float lam, float lam_init, float M0, unsigned* ctr, LAS int* s_unit, int wid_s_) {
;     ...
;         const int Tlo = tlo >> 1, Thi = thi >> 1;
;         ATT_DMA(2 * Tlo, 0); ATT_DMA(2 * Tlo + 1, 1);
;         for (int T = Tlo; T <= Thi; ++T) {
;             const int b = (T - Tlo) & 1;
;             asm volatile("s_waitcnt vmcnt(0)" ::: "memory");
;             __syncthreads();
;             if (T + 1 <= Thi) { ATT_DMA(2 * T + 2, 2 * (b ^ 1)); ATT_DMA(2 * T + 3, 2 * (b ^ 1) + 1); }
.LBB0_1309:
	s_bitcmp1_b32 s37, 12
	s_cbranch_scc0 .Ldma_mid_skip
	s_add_i32 s2, s15, s49
	s_cmp_lt_i32 s2, s48
	s_cbranch_scc0 .Ldma_mid_skip
	s_and_b32 s2, s49, 1
	s_lshl_b32 s2, s2, 16
	s_xor_b32 s2, s2, 0x10000
	s_add_i32 s2, s37, s2
	v_lshl_add_u64 v[64:65], s[28:29], 0, v[182:183]
	v_lshl_add_u64 v[66:67], v[64:65], 0, s[68:69]
	s_mov_b32 m0, s2
	v_lshl_add_u64 v[64:65], v[64:65], 0, s[72:73]
	global_load_lds_dwordx4 v[66:67], off
	v_lshl_add_u64 v[66:67], s[28:29], 0, v[180:181]
	v_lshl_add_u64 v[68:69], v[66:67], 0, s[68:69]
	s_add_i32 m0, s2, 0x2000
	s_nop 0
	global_load_lds_dwordx4 v[68:69], off
	v_lshl_add_u64 v[68:69], s[28:29], 0, v[178:179]
	s_add_i32 m0, s2, 0x4000
	v_lshl_add_u64 v[70:71], v[68:69], 0, s[70:71]
	global_load_lds_dwordx4 v[70:71], off
	v_lshl_add_u64 v[70:71], s[28:29], 0, v[176:177]
	v_lshl_add_u64 v[72:73], v[70:71], 0, s[70:71]
	s_add_i32 m0, s2, 0x6000
	s_nop 0
	global_load_lds_dwordx4 v[72:73], off
	s_add_i32 m0, s2, 0x8000
	s_nop 0
	global_load_lds_dwordx4 v[64:65], off
	v_lshl_add_u64 v[64:65], v[66:67], 0, s[72:73]
	s_add_i32 m0, s2, 0xa000
	s_nop 0
	global_load_lds_dwordx4 v[64:65], off
	s_add_i32 m0, s2, 0xc000
	v_lshl_add_u64 v[64:65], v[68:69], 0, s[76:77]
	global_load_lds_dwordx4 v[64:65], off
	v_lshl_add_u64 v[64:65], v[70:71], 0, s[76:77]
	s_add_i32 m0, s2, 0xe000
	s_nop 0
	global_load_lds_dwordx4 v[64:65], off
